# P5 compressed-branch QK sites (2): six-deep K-fragment ring with counted lgkmcnt waits instead of one buffer and a full LDS round trip per MFMA
# baseline (speedup 1.0000x reference)
; template <int KB, bool SK>
; __device__ __forceinline__ void qkt(f32x16& p0, f32x16& p1, const char* K_lds, int r32, int hi, const bf16x8* qr, bool act) {
;     if (SK && !act) return;
;     p0 = f32x16{}; p1 = f32x16{};
;     const char* kb[4];
; #pragma unroll
;     for (int dd = 0; dd < 4; ++dd) kb[dd] = K_lds + KB * SHM_K + KSWZ(r32, (dd * 16 + hi * 8) * 2);
; #pragma unroll
;     for (int d0 = 0; d0 < 8; ++d0) { const char* a = kb[d0 & 3] + (d0 >> 2) * 128;
;         bf16x8 b0 = *reinterpret_cast<const bf16x8*>(a);
;         bf16x8 b1 = *reinterpret_cast<const bf16x8*>(a + 32 * 256);
;         p0 = __builtin_amdgcn_mfma_f32_32x32x16_bf16(b0, qr[d0], p0, 0, 0, 0);
;         p1 = __builtin_amdgcn_mfma_f32_32x32x16_bf16(b1, qr[d0], p1, 0, 0, 0); }
; }
; __device__ __forceinline__ void cmp_item(char* lds, unsigned char* wsb, float* d_oc_, int b, int g, int qb, const int wid) {
;     ...
;         qkt<0, false>(p0, p1, K_lds, r32, hi, qr, true);
;         if (1024 * j + 1152 > t0 + wid * 8) cmp_bias_mask(p0, p1, t - 31 - 16 * (64 * j + 4 * hi), tb);
.LBB0_1016:
	s_cmpk_lt_u32 s65, 0xee
	ds_read_b128 v[208:211], v178 offset:32768
	ds_read_b128 v[212:215], v178 offset:40960
	ds_read_b128 v[216:219], v179 offset:32768
	ds_read_b128 v[220:223], v179 offset:40960
	ds_read_b128 v[224:227], v180 offset:32768
	ds_read_b128 v[228:231], v180 offset:40960
	s_waitcnt lgkmcnt(5)
	v_mfma_f32_32x32x16_bf16 v[16:31], v[208:211], v[112:115], 0
	ds_read_b128 v[208:211], v181 offset:32768
	s_waitcnt lgkmcnt(5)
	v_mfma_f32_32x32x16_bf16 v[0:15], v[212:215], v[112:115], 0
	ds_read_b128 v[212:215], v181 offset:40960
	s_waitcnt lgkmcnt(5)
	v_mfma_f32_32x32x16_bf16 v[16:31], v[216:219], v[116:119], v[16:31]
	ds_read_b128 v[216:219], v178 offset:32896
	s_waitcnt lgkmcnt(5)
	v_mfma_f32_32x32x16_bf16 v[0:15], v[220:223], v[116:119], v[0:15]
	ds_read_b128 v[220:223], v178 offset:41088
	s_waitcnt lgkmcnt(5)
	v_mfma_f32_32x32x16_bf16 v[16:31], v[224:227], v[120:123], v[16:31]
	ds_read_b128 v[224:227], v179 offset:32896
	s_waitcnt lgkmcnt(5)
	v_mfma_f32_32x32x16_bf16 v[0:15], v[228:231], v[120:123], v[0:15]
	ds_read_b128 v[228:231], v179 offset:41088
	s_waitcnt lgkmcnt(5)
	v_mfma_f32_32x32x16_bf16 v[16:31], v[208:211], v[124:127], v[16:31]
	ds_read_b128 v[208:211], v180 offset:32896
	s_waitcnt lgkmcnt(5)
	v_mfma_f32_32x32x16_bf16 v[0:15], v[212:215], v[124:127], v[0:15]
	ds_read_b128 v[212:215], v180 offset:41088
	s_waitcnt lgkmcnt(5)
	v_mfma_f32_32x32x16_bf16 v[16:31], v[216:219], v[128:131], v[16:31]
	ds_read_b128 v[216:219], v181 offset:32896
	s_waitcnt lgkmcnt(5)
	v_mfma_f32_32x32x16_bf16 v[0:15], v[220:223], v[128:131], v[0:15]
	ds_read_b128 v[220:223], v181 offset:41088
	s_waitcnt lgkmcnt(5)
	v_mfma_f32_32x32x16_bf16 v[16:31], v[224:227], v[132:135], v[16:31]
	s_waitcnt lgkmcnt(4)
	v_mfma_f32_32x32x16_bf16 v[0:15], v[228:231], v[132:135], v[0:15]
	s_waitcnt lgkmcnt(3)
	v_mfma_f32_32x32x16_bf16 v[16:31], v[208:211], v[136:139], v[16:31]
	s_waitcnt lgkmcnt(2)
	v_mfma_f32_32x32x16_bf16 v[0:15], v[212:215], v[136:139], v[0:15]
	s_waitcnt lgkmcnt(1)
	v_mfma_f32_32x32x16_bf16 v[16:31], v[216:219], v[140:143], v[16:31]
	s_waitcnt lgkmcnt(0)
	v_mfma_f32_32x32x16_bf16 v[0:15], v[220:223], v[140:143], v[0:15]
	s_cbranch_scc1 .LBB0_1050
	v_sub_u32_e32 v32, v53, v67
	v_add_u32_e32 v33, 0xfffffde1, v32
	v_min_u32_e32 v33, 0x7f, v33
	v_lshl_add_u32 v33, v33, 2, v176
	ds_read_b32 v50, v33
	v_subrev_u32_e32 v48, 31, v32
	v_cmp_lt_i32_e32 vcc, -1, v48
	v_mov_b32_e32 v33, 0xff800000
	v_mov_b32_e32 v32, 0xff800000
	s_and_saveexec_b64 s[2:3], vcc
	s_cbranch_execz .LBB0_1019
	v_min_u32_e32 v32, 0x7f, v48
	v_lshl_add_u32 v32, v32, 2, v176
	ds_read_b32 v32, v32
	s_waitcnt lgkmcnt(0)
	v_add_f32_e32 v32, v16, v32

; template <int KB, bool SK>
; __device__ __forceinline__ void qkt(f32x16& p0, f32x16& p1, const char* K_lds, int r32, int hi, const bf16x8* qr, bool act) {
;     if (SK && !act) return;
;     p0 = f32x16{}; p1 = f32x16{};
;     const char* kb[4];
; #pragma unroll
;     for (int dd = 0; dd < 4; ++dd) kb[dd] = K_lds + KB * SHM_K + KSWZ(r32, (dd * 16 + hi * 8) * 2);
; #pragma unroll
;     for (int d0 = 0; d0 < 8; ++d0) { const char* a = kb[d0 & 3] + (d0 >> 2) * 128;
;         bf16x8 b0 = *reinterpret_cast<const bf16x8*>(a);
;         bf16x8 b1 = *reinterpret_cast<const bf16x8*>(a + 32 * 256);
;         p0 = __builtin_amdgcn_mfma_f32_32x32x16_bf16(b0, qr[d0], p0, 0, 0, 0);
;         p1 = __builtin_amdgcn_mfma_f32_32x32x16_bf16(b1, qr[d0], p1, 0, 0, 0); }
; }
; __device__ __forceinline__ void cmp_item(char* lds, unsigned char* wsb, float* d_oc_, int b, int g, int qb, const int wid) {
;     ...
;         qkt<0, false>(p0, p1, K_lds, r32, hi, qr, true);
;         if (1024 * j + 1152 > t0 + wid * 8) cmp_bias_mask(p0, p1, t - 31 - 16 * (64 * j + 4 * hi), tb);
.LBB0_1057:
	s_cmp_le_u32 s20, s54
	ds_read_b128 v[208:211], v178 offset:32768
	ds_read_b128 v[212:215], v178 offset:40960
	ds_read_b128 v[216:219], v179 offset:32768
	ds_read_b128 v[220:223], v179 offset:40960
	ds_read_b128 v[224:227], v180 offset:32768
	ds_read_b128 v[228:231], v180 offset:40960
	s_waitcnt lgkmcnt(5)
	v_mfma_f32_32x32x16_bf16 v[80:95], v[208:211], v[112:115], 0
	ds_read_b128 v[208:211], v181 offset:32768
	s_waitcnt lgkmcnt(5)
	v_mfma_f32_32x32x16_bf16 v[64:79], v[212:215], v[112:115], 0
	ds_read_b128 v[212:215], v181 offset:40960
	s_waitcnt lgkmcnt(5)
	v_mfma_f32_32x32x16_bf16 v[80:95], v[216:219], v[116:119], v[80:95]
	ds_read_b128 v[216:219], v178 offset:32896
	s_waitcnt lgkmcnt(5)
	v_mfma_f32_32x32x16_bf16 v[64:79], v[220:223], v[116:119], v[64:79]
	ds_read_b128 v[220:223], v178 offset:41088
	s_waitcnt lgkmcnt(5)
	v_mfma_f32_32x32x16_bf16 v[80:95], v[224:227], v[120:123], v[80:95]
	ds_read_b128 v[224:227], v179 offset:32896
	s_waitcnt lgkmcnt(5)
	v_mfma_f32_32x32x16_bf16 v[64:79], v[228:231], v[120:123], v[64:79]
	ds_read_b128 v[228:231], v179 offset:41088
	s_waitcnt lgkmcnt(5)
	v_mfma_f32_32x32x16_bf16 v[80:95], v[208:211], v[124:127], v[80:95]
	ds_read_b128 v[208:211], v180 offset:32896
	s_waitcnt lgkmcnt(5)
	v_mfma_f32_32x32x16_bf16 v[64:79], v[212:215], v[124:127], v[64:79]
	ds_read_b128 v[212:215], v180 offset:41088
	s_waitcnt lgkmcnt(5)
	v_mfma_f32_32x32x16_bf16 v[80:95], v[216:219], v[128:131], v[80:95]
	ds_read_b128 v[216:219], v181 offset:32896
	s_waitcnt lgkmcnt(5)
	v_mfma_f32_32x32x16_bf16 v[64:79], v[220:223], v[128:131], v[64:79]
	ds_read_b128 v[220:223], v181 offset:41088
	s_waitcnt lgkmcnt(5)
	v_mfma_f32_32x32x16_bf16 v[80:95], v[224:227], v[132:135], v[80:95]
	s_waitcnt lgkmcnt(4)
	v_mfma_f32_32x32x16_bf16 v[64:79], v[228:231], v[132:135], v[64:79]
	s_waitcnt lgkmcnt(3)
	v_mfma_f32_32x32x16_bf16 v[80:95], v[208:211], v[136:139], v[80:95]
	s_waitcnt lgkmcnt(2)
	v_mfma_f32_32x32x16_bf16 v[64:79], v[212:215], v[136:139], v[64:79]
	s_waitcnt lgkmcnt(1)
	v_mfma_f32_32x32x16_bf16 v[80:95], v[216:219], v[140:143], v[80:95]
	s_waitcnt lgkmcnt(0)
	v_mfma_f32_32x32x16_bf16 v[64:79], v[220:223], v[140:143], v[64:79]
	s_cbranch_scc1 .LBB0_1091
	v_add_u32_e32 v96, 0xfffffe00, v189
	v_min_u32_e32 v96, 0x7f, v96
	v_lshl_add_u32 v96, v96, 2, v176
	ds_read_b32 v160, v96
	v_cmp_lt_i32_e64 s[8:9], -1, v189
	v_mov_b32_e32 v97, 0xff800000
	v_mov_b32_e32 v96, 0xff800000
	s_and_saveexec_b64 s[62:63], s[8:9]
	s_cbranch_execz .LBB0_1060
	v_min_u32_e32 v96, 0x7f, v189
	v_lshl_add_u32 v96, v96, 2, v176
	ds_read_b32 v96, v96
	s_waitcnt lgkmcnt(0)
	v_add_f32_e32 v96, v80, v96
